# GEMM main loop bodies aligned to 64 bytes
# speedup vs baseline: 1.0059x; 1.0059x over previous
; __device__ __forceinline__ int prow0(int pm) { return (pm >> 4) * LP + PADR + (pm & 15) * 256; }
; template <class Epi>
; __device__ __forceinline__ void gemm_phase(LAS unsigned char* lds, const bf16_t* Ag, const bf16_t* Btg, const int K, const int nM, const int nN, const Epi& E) {
;     ...
;         const int un = u + G; const bool has_next = un < nunits; const int pmn = has_next ? un % nM : pm, pnn = has_next ? un / nM : pn;
;         const char* nA = has_next ? (const char*)Ag + (size_t)prow0(pmn) * rstep : cA; const char* nB = has_next ? (const char*)Btg + (size_t)pnn * tstep : cB;
;         for (int t = 0; t < nt; t += 2) {
;             const bool last = (t == nt - 2);
;             const char* a1 = cA + (size_t)(t + 1) * kstep;
;             const char* a2 = last ? nA : cA + (size_t)(t + 2) * kstep; const char* b2 = last ? nB : cB + (size_t)(t + 2) * kstep;
;     ...
; #pragma unroll
;         for (int a = 0; a < 2; ++a)
; #pragma unroll
;             for (int b = 0; b < 2; ++b)
; #pragma unroll
;                 for (int m = 0; m < 4; ++m)
; #pragma unroll
;                     for (int n = 0; n < 2; ++n) acc[a][b][m][n] = (f32x4){0.f, 0.f, 0.f, 0.f};
;         if (pmn != pm) par ^= 1;
;         u = un; pm = pmn; pn = pnn; cA = nA; cB = nB;
.LBB0_76:
	s_ashr_i32 s47, s12, 6
	s_and_b64 s[14:15], s[48:49], exec
	s_cselect_b32 s14, s68, s47
	s_ashr_i32 s15, s14, 31
	s_lshl_b64 s[14:15], s[14:15], 19
	s_add_u32 s44, s24, s14
	s_addc_u32 s45, s25, s15
	s_and_b64 s[14:15], s[48:49], exec
	s_cselect_b32 s15, s53, s45
	s_cselect_b32 s69, s52, s44
	s_cmp_eq_u32 s67, s66
	s_cselect_b64 s[54:55], -1, 0
	s_lshl_b32 s14, s64, 11
	s_xor_b32 s12, s14, 0x800
	s_add_i32 s70, s12, 0
	s_add_i32 s70, s70, 0x20000
	s_or_b64 s[48:49], s[48:49], s[54:55]
	s_add_u32 s71, s52, 0x100
	s_addc_u32 s72, s53, 0
	s_add_u32 s50, s50, 0x40080
	v_mov_b32_e32 v8, 0
	s_addc_u32 s51, s51, 0
	s_mov_b32 s73, -2
	v_mov_b32_e32 v9, v8
	v_mov_b32_e32 v10, v8
	v_mov_b32_e32 v11, v8
	v_mov_b32_e32 v12, v8
	v_mov_b32_e32 v13, v8
	v_mov_b32_e32 v14, v8
	v_mov_b32_e32 v15, v8
	v_mov_b32_e32 v24, v8
	v_mov_b32_e32 v25, v8
	v_mov_b32_e32 v26, v8
	v_mov_b32_e32 v27, v8
	v_mov_b32_e32 v28, v8
	v_mov_b32_e32 v29, v8
	v_mov_b32_e32 v30, v8
	v_mov_b32_e32 v31, v8
	v_mov_b32_e32 v40, v8
	v_mov_b32_e32 v41, v8
	v_mov_b32_e32 v42, v8
	v_mov_b32_e32 v43, v8
	v_mov_b32_e32 v44, v8
	v_mov_b32_e32 v45, v8
	v_mov_b32_e32 v46, v8
	v_mov_b32_e32 v47, v8
	v_mov_b32_e32 v56, v8
	v_mov_b32_e32 v57, v8
	v_mov_b32_e32 v58, v8
	v_mov_b32_e32 v59, v8
	v_mov_b32_e32 v60, v8
	v_mov_b32_e32 v61, v8
	v_mov_b32_e32 v62, v8
	v_mov_b32_e32 v63, v8
	v_mov_b32_e32 v72, v8
	v_mov_b32_e32 v73, v8
	v_mov_b32_e32 v74, v8
	v_mov_b32_e32 v75, v8
	v_mov_b32_e32 v76, v8
	v_mov_b32_e32 v77, v8
	v_mov_b32_e32 v78, v8
	v_mov_b32_e32 v79, v8
	v_mov_b32_e32 v88, v8
	v_mov_b32_e32 v89, v8
	v_mov_b32_e32 v90, v8
	v_mov_b32_e32 v91, v8
	v_mov_b32_e32 v92, v8
	v_mov_b32_e32 v93, v8
	v_mov_b32_e32 v94, v8
	v_mov_b32_e32 v95, v8
	v_mov_b32_e32 v104, v8
	v_mov_b32_e32 v105, v8
	v_mov_b32_e32 v106, v8
	v_mov_b32_e32 v107, v8
	v_mov_b32_e32 v108, v8
	v_mov_b32_e32 v109, v8
	v_mov_b32_e32 v110, v8
	v_mov_b32_e32 v111, v8
	v_mov_b32_e32 v120, v8
	v_mov_b32_e32 v121, v8
	v_mov_b32_e32 v122, v8
	v_mov_b32_e32 v123, v8
	v_mov_b32_e32 v144, v8
	v_mov_b32_e32 v145, v8
	v_mov_b32_e32 v146, v8
	v_mov_b32_e32 v147, v8
	v_mov_b32_e32 v80, v8
	v_mov_b32_e32 v81, v8
	v_mov_b32_e32 v82, v8
	v_mov_b32_e32 v83, v8
	v_mov_b32_e32 v84, v8
	v_mov_b32_e32 v85, v8
	v_mov_b32_e32 v86, v8
	v_mov_b32_e32 v87, v8
	v_mov_b32_e32 v96, v8
	v_mov_b32_e32 v97, v8
	v_mov_b32_e32 v98, v8
	v_mov_b32_e32 v99, v8
	v_mov_b32_e32 v100, v8
	v_mov_b32_e32 v101, v8
	v_mov_b32_e32 v102, v8
	v_mov_b32_e32 v103, v8
	v_mov_b32_e32 v112, v8
	v_mov_b32_e32 v113, v8
	v_mov_b32_e32 v114, v8
	v_mov_b32_e32 v115, v8
	v_mov_b32_e32 v116, v8
	v_mov_b32_e32 v117, v8
	v_mov_b32_e32 v118, v8
	v_mov_b32_e32 v119, v8
	v_mov_b32_e32 v160, v8
	v_mov_b32_e32 v161, v8
	v_mov_b32_e32 v162, v8
	v_mov_b32_e32 v163, v8
	v_mov_b32_e32 v164, v8
	v_mov_b32_e32 v165, v8
	v_mov_b32_e32 v166, v8
	v_mov_b32_e32 v167, v8
	v_mov_b32_e32 v68, v8
	v_mov_b32_e32 v69, v8
	v_mov_b32_e32 v70, v8
	v_mov_b32_e32 v71, v8
	v_mov_b32_e32 v64, v8
	v_mov_b32_e32 v65, v8
	v_mov_b32_e32 v66, v8
	v_mov_b32_e32 v67, v8
	v_mov_b32_e32 v52, v8
	v_mov_b32_e32 v53, v8
	v_mov_b32_e32 v54, v8
	v_mov_b32_e32 v55, v8
	v_mov_b32_e32 v48, v8
	v_mov_b32_e32 v49, v8
	v_mov_b32_e32 v50, v8
	v_mov_b32_e32 v51, v8
	v_mov_b32_e32 v36, v8
	v_mov_b32_e32 v37, v8
	v_mov_b32_e32 v38, v8
	v_mov_b32_e32 v39, v8
	v_mov_b32_e32 v32, v8
	v_mov_b32_e32 v33, v8
	v_mov_b32_e32 v34, v8
	v_mov_b32_e32 v35, v8
	v_mov_b32_e32 v20, v8
	v_mov_b32_e32 v21, v8
	v_mov_b32_e32 v22, v8
	v_mov_b32_e32 v23, v8
	v_mov_b32_e32 v16, v8
	v_mov_b32_e32 v17, v8
	v_mov_b32_e32 v18, v8
	v_mov_b32_e32 v19, v8
	s_branch .LBB0_79
	.p2align 6

;     __device__ __forceinline__ void prep(int pm, int par, LAS unsigned char* lds) const { if (fold) prep_rowstats(stat, pm, par, lds); }
;     __device__ __forceinline__ void prep(int pm, int par, LAS unsigned char* lds) const { if (!ident) prep_rowstats(stat, pm, par, lds); }
;     __device__ __forceinline__ void prep(int pm, int par, LAS unsigned char* lds) const { prep_rowstats(stat, pm, par, lds); }
; #define G_STAGE(bufoff, gbase) do { _Pragma("unroll") for (int _i = 0; _i < 2; ++_i) \
;         __builtin_amdgcn_global_load_lds((const unsigned*)((const char*)(gbase) + voff[_i]), (LAS unsigned*)(lds + (bufoff) + ldsw + _i * 8192), 16, 0, 0); } while (0)
; #define G_LDA(dst, b, h) do { _Pragma("unroll") for (int m = 0; m < 4; ++m) _Pragma("unroll") for (int k = 0; k < 2; ++k) dst[m][k] = *(const LAS bf16x8*)(lds + G_SA(b, h) + aoff + m * 2048 + k * 1024); } while (0)
; #define G_LDB(dst, b, h) do { _Pragma("unroll") for (int n = 0; n < 2; ++n) _Pragma("unroll") for (int k = 0; k < 2; ++k) dst[n][k] = *(const LAS bf16x8*)(lds + G_SB(b, h) + boff + n * 2048 + k * 1024); } while (0)
; #define G_SCHED __builtin_amdgcn_sched_barrier(0)
; template <class Epi>
; __device__ __forceinline__ void gemm_phase(LAS unsigned char* lds, const bf16_t* Ag, const bf16_t* Btg, const int K, const int nM, const int nN, const Epi& E) {
;     ...
;         for (int t = 0; t < nt; t += 2) {
;             const bool last = (t == nt - 2);
;             const char* a1 = cA + (size_t)(t + 1) * kstep;
;             const char* a2 = last ? nA : cA + (size_t)(t + 2) * kstep; const char* b2 = last ? nB : cB + (size_t)(t + 2) * kstep;
;             const char* a3 = a2 + kstep; const char* b3 = b2 + kstep;
;             if (last && has_next && pmn != pm) E.prep(pmn, par ^ 1, lds);
;             G_LDB(B0, 0, 0); G_SCHED; G_LDA(At, 0, 0); G_STAGE(G_SA(1, 1), a1 + hstep);
.LBB0_152:
	s_or_b64 exec, exec, s[66:67]
	.p2align 6

;     __device__ __forceinline__ void prep(int pm, int par, LAS unsigned char* lds) const { if (fold) prep_rowstats(stat, pm, par, lds); }
;     __device__ __forceinline__ void prep(int pm, int par, LAS unsigned char* lds) const { if (!ident) prep_rowstats(stat, pm, par, lds); }
;     __device__ __forceinline__ void prep(int pm, int par, LAS unsigned char* lds) const { prep_rowstats(stat, pm, par, lds); }
; #define G_STAGE(bufoff, gbase) do { _Pragma("unroll") for (int _i = 0; _i < 2; ++_i) \
;         __builtin_amdgcn_global_load_lds((const unsigned*)((const char*)(gbase) + voff[_i]), (LAS unsigned*)(lds + (bufoff) + ldsw + _i * 8192), 16, 0, 0); } while (0)
; #define G_LDA(dst, b, h) do { _Pragma("unroll") for (int m = 0; m < 4; ++m) _Pragma("unroll") for (int k = 0; k < 2; ++k) dst[m][k] = *(const LAS bf16x8*)(lds + G_SA(b, h) + aoff + m * 2048 + k * 1024); } while (0)
; #define G_LDB(dst, b, h) do { _Pragma("unroll") for (int n = 0; n < 2; ++n) _Pragma("unroll") for (int k = 0; k < 2; ++k) dst[n][k] = *(const LAS bf16x8*)(lds + G_SB(b, h) + boff + n * 2048 + k * 1024); } while (0)
; #define G_SCHED __builtin_amdgcn_sched_barrier(0)
; template <class Epi>
; __device__ __forceinline__ void gemm_phase(LAS unsigned char* lds, const bf16_t* Ag, const bf16_t* Btg, const int K, const int nM, const int nN, const Epi& E) {
;     ...
;         for (int t = 0; t < nt; t += 2) {
;             const bool last = (t == nt - 2);
;             const char* a1 = cA + (size_t)(t + 1) * kstep;
;             const char* a2 = last ? nA : cA + (size_t)(t + 2) * kstep; const char* b2 = last ? nB : cB + (size_t)(t + 2) * kstep;
;             const char* a3 = a2 + kstep; const char* b3 = b2 + kstep;
;             if (last && has_next && pmn != pm) E.prep(pmn, par ^ 1, lds);
;             G_LDB(B0, 0, 0); G_SCHED; G_LDA(At, 0, 0); G_STAGE(G_SA(1, 1), a1 + hstep);
.LBB0_743:
	s_or_b64 exec, exec, s[58:59]
	.p2align 6

; __device__ __forceinline__ int prow0(int pm) { return (pm >> 4) * LP + PADR + (pm & 15) * 256; }
; template <class Epi>
; __device__ __forceinline__ void gemm_phase(LAS unsigned char* lds, const bf16_t* Ag, const bf16_t* Btg, const int K, const int nM, const int nN, const Epi& E) {
;     ...
;         const int un = u + G; const bool has_next = un < nunits; const int pmn = has_next ? un % nM : pm, pnn = has_next ? un / nM : pn;
;         const char* nA = has_next ? (const char*)Ag + (size_t)prow0(pmn) * rstep : cA; const char* nB = has_next ? (const char*)Btg + (size_t)pnn * tstep : cB;
;         for (int t = 0; t < nt; t += 2) {
;             const bool last = (t == nt - 2);
;             const char* a1 = cA + (size_t)(t + 1) * kstep;
;             const char* a2 = last ? nA : cA + (size_t)(t + 2) * kstep; const char* b2 = last ? nB : cB + (size_t)(t + 2) * kstep;
;     ...
; #pragma unroll
;         for (int a = 0; a < 2; ++a)
; #pragma unroll
;             for (int b = 0; b < 2; ++b)
; #pragma unroll
;                 for (int m = 0; m < 4; ++m)
; #pragma unroll
;                     for (int n = 0; n < 2; ++n) acc[a][b][m][n] = (f32x4){0.f, 0.f, 0.f, 0.f};
;         if (pmn != pm) par ^= 1;
;         u = un; pm = pmn; pn = pnn; cA = nA; cB = nB;
.LBB0_846:
	s_ashr_i32 s47, s26, 6
	s_and_b64 s[14:15], s[48:49], exec
	s_cselect_b32 s14, s69, s47
	s_ashr_i32 s15, s14, 31
	s_lshl_b64 s[14:15], s[14:15], 19
	s_add_u32 s44, s6, s14
	s_addc_u32 s45, s7, s15
	s_and_b64 s[14:15], s[48:49], exec
	s_cselect_b32 s14, s53, s45
	s_cselect_b32 s15, s52, s44
	s_cmp_eq_u32 s67, s68
	s_cselect_b64 s[54:55], -1, 0
	s_or_b64 s[54:55], s[42:43], s[54:55]
	v_lshlrev_b32_e32 v174, 11, v223
	s_or_b64 s[48:49], s[48:49], s[54:55]
	v_xor_b32_e32 v8, 0x800, v174
	s_add_u32 s70, s52, 0x100
	v_add_u32_e32 v8, 0, v8
	s_addc_u32 s71, s53, 0
	v_add_u32_e32 v128, 0x20000, v8
	s_add_u32 s50, s50, 0x40080
	v_mov_b32_e32 v8, 0
	s_addc_u32 s51, s51, 0
	s_mov_b32 s72, -2
	v_mov_b32_e32 v9, v8
	v_mov_b32_e32 v10, v8
	v_mov_b32_e32 v11, v8
	v_mov_b32_e32 v12, v8
	v_mov_b32_e32 v13, v8
	v_mov_b32_e32 v14, v8
	v_mov_b32_e32 v15, v8
	v_mov_b32_e32 v24, v8
	v_mov_b32_e32 v25, v8
	v_mov_b32_e32 v26, v8
	v_mov_b32_e32 v27, v8
	v_mov_b32_e32 v28, v8
	v_mov_b32_e32 v29, v8
	v_mov_b32_e32 v30, v8
	v_mov_b32_e32 v31, v8
	v_mov_b32_e32 v40, v8
	v_mov_b32_e32 v41, v8
	v_mov_b32_e32 v42, v8
	v_mov_b32_e32 v43, v8
	v_mov_b32_e32 v44, v8
	v_mov_b32_e32 v45, v8
	v_mov_b32_e32 v46, v8
	v_mov_b32_e32 v47, v8
	v_mov_b32_e32 v56, v8
	v_mov_b32_e32 v57, v8
	v_mov_b32_e32 v58, v8
	v_mov_b32_e32 v59, v8
	v_mov_b32_e32 v60, v8
	v_mov_b32_e32 v61, v8
	v_mov_b32_e32 v62, v8
	v_mov_b32_e32 v63, v8
	v_mov_b32_e32 v72, v8
	v_mov_b32_e32 v73, v8
	v_mov_b32_e32 v74, v8
	v_mov_b32_e32 v75, v8
	v_mov_b32_e32 v76, v8
	v_mov_b32_e32 v77, v8
	v_mov_b32_e32 v78, v8
	v_mov_b32_e32 v79, v8
	v_mov_b32_e32 v88, v8
	v_mov_b32_e32 v89, v8
	v_mov_b32_e32 v90, v8
	v_mov_b32_e32 v91, v8
	v_mov_b32_e32 v92, v8
	v_mov_b32_e32 v93, v8
	v_mov_b32_e32 v94, v8
	v_mov_b32_e32 v95, v8
	v_mov_b32_e32 v104, v8
	v_mov_b32_e32 v105, v8
	v_mov_b32_e32 v106, v8
	v_mov_b32_e32 v107, v8
	v_mov_b32_e32 v108, v8
	v_mov_b32_e32 v109, v8
	v_mov_b32_e32 v110, v8
	v_mov_b32_e32 v111, v8
	v_mov_b32_e32 v120, v8
	v_mov_b32_e32 v121, v8
	v_mov_b32_e32 v122, v8
	v_mov_b32_e32 v123, v8
	v_mov_b32_e32 v124, v8
	v_mov_b32_e32 v125, v8
	v_mov_b32_e32 v126, v8
	v_mov_b32_e32 v127, v8
	v_mov_b32_e32 v80, v8
	v_mov_b32_e32 v81, v8
	v_mov_b32_e32 v82, v8
	v_mov_b32_e32 v83, v8
	v_mov_b32_e32 v84, v8
	v_mov_b32_e32 v85, v8
	v_mov_b32_e32 v86, v8
	v_mov_b32_e32 v87, v8
	v_mov_b32_e32 v96, v8
	v_mov_b32_e32 v97, v8
	v_mov_b32_e32 v98, v8
	v_mov_b32_e32 v99, v8
	v_mov_b32_e32 v100, v8
	v_mov_b32_e32 v101, v8
	v_mov_b32_e32 v102, v8
	v_mov_b32_e32 v103, v8
	v_mov_b32_e32 v112, v8
	v_mov_b32_e32 v113, v8
	v_mov_b32_e32 v114, v8
	v_mov_b32_e32 v115, v8
	v_mov_b32_e32 v116, v8
	v_mov_b32_e32 v117, v8
	v_mov_b32_e32 v118, v8
	v_mov_b32_e32 v119, v8
	v_mov_b32_e32 v140, v8
	v_mov_b32_e32 v141, v8
	v_mov_b32_e32 v142, v8
	v_mov_b32_e32 v143, v8
	v_mov_b32_e32 v152, v8
	v_mov_b32_e32 v153, v8
	v_mov_b32_e32 v154, v8
	v_mov_b32_e32 v155, v8
	v_mov_b32_e32 v68, v8
	v_mov_b32_e32 v69, v8
	v_mov_b32_e32 v70, v8
	v_mov_b32_e32 v71, v8
	v_mov_b32_e32 v64, v8
	v_mov_b32_e32 v65, v8
	v_mov_b32_e32 v66, v8
	v_mov_b32_e32 v67, v8
	v_mov_b32_e32 v52, v8
	v_mov_b32_e32 v53, v8
	v_mov_b32_e32 v54, v8
	v_mov_b32_e32 v55, v8
	v_mov_b32_e32 v48, v8
	v_mov_b32_e32 v49, v8
	v_mov_b32_e32 v50, v8
	v_mov_b32_e32 v51, v8
	v_mov_b32_e32 v36, v8
	v_mov_b32_e32 v37, v8
	v_mov_b32_e32 v38, v8
	v_mov_b32_e32 v39, v8
	v_mov_b32_e32 v32, v8
	v_mov_b32_e32 v33, v8
	v_mov_b32_e32 v34, v8
	v_mov_b32_e32 v35, v8
	v_mov_b32_e32 v20, v8
	v_mov_b32_e32 v21, v8
	v_mov_b32_e32 v22, v8
	v_mov_b32_e32 v23, v8
	v_mov_b32_e32 v16, v8
	v_mov_b32_e32 v17, v8
	v_mov_b32_e32 v18, v8
	v_mov_b32_e32 v19, v8
	s_branch .LBB0_849
	.p2align 6
